# dn_prep stage 3 idle waves: next-item L2 prefetch loads land in unused registers, no wait before the barrier
# speedup vs baseline: 1.0127x; 1.0003x over previous
; #define LAS __attribute__((address_space(3)))
; __device__ __forceinline__ float bf2f(unsigned short v) { return __uint_as_float(((unsigned)v) << 16); }
; __device__ __forceinline__ unsigned pk2(float lo, float hi) { const f32x2_t v = {lo, hi}; const bf16x2_t b = __builtin_convertvector(v, bf16x2_t); return __builtin_bit_cast(unsigned, b); }
; __device__ __forceinline__ void dn_prep_item(const Args& a, LAS unsigned char* lds, int item, int tid, int wave, int lane, int& cwh, int next_item) {
;     ...
;         const int t2 = tid - 256; const float gl = gcs[63];
; #pragma unroll 4
;         for (int r = 0; r < 32; ++r) { const int idx = t2 + 256 * r, i = idx & 63, d = idx >> 6;
;             const float v = bf2f(*(const LAS unsigned short*)(lds + L_KH + i * KS_ + 2 * d)) * __expf(gl - gcs[i]);
;             *(LAS unsigned short*)(lds + L_KDT + d * AS_ + 2 * i) = (unsigned short)(pk2(v, 0.f) & 0xffffu); }
;         if (next_item >= 0) { const int h2 = next_item & 3, n2 = (next_item >> 2) & (NCH - 1), b2 = next_item >> 9; unsigned d0 = 0u, d1 = 0u;
;             const unsigned char* pb = (const unsigned char*)(P + (size_t)(b2 * T + n2 * 64) * NIN + 1024 + h2 * 128);
;             { const int idx = t2, row = idx / 6, seg = idx % 6; if (n2 > 0 || row >= 3) asm volatile("global_load_dword %0, %1, off" : "+v"(d0) : "v"(pb + (ptrdiff_t)(row - 3) * (NIN * 2) + (seg >> 1) * 1024 + (seg & 1) * 128) : "memory"); }
;             { const int idx = t2 + 256, row = idx / 6, seg = idx % 6; if (idx < 402) asm volatile("global_load_dword %0, %1, off" : "+v"(d1) : "v"(pb + (ptrdiff_t)(row - 3) * (NIN * 2) + (seg >> 1) * 1024 + (seg & 1) * 128) : "memory"); }
;             asm volatile("s_waitcnt vmcnt(0)" ::: "memory"); asm volatile("" :: "v"(d0), "v"(d1)); }
.LBB0_870:
	v_add_u32_e32 v1, s22, v206
	v_add_u32_e32 v2, 0xffffff00, v1
	v_ashrrev_i32_e32 v2, 6, v2
	v_lshl_add_u32 v3, v2, 1, v187
	ds_read_u16 v3, v3
	s_addk_i32 s22, 0x400
	s_cmpk_eq_i32 s22, 0x2000
	s_waitcnt lgkmcnt(0)
	v_lshlrev_b32_e32 v3, 16, v3
	v_mul_f32_e32 v3, v0, v3
	v_cvt_pk_bf16_f32 v4, v3, s0
	v_mad_u64_u32 v[2:3], s[42:43], v2, s24, v[48:49]
	ds_write_b16 v2, v4
	v_ashrrev_i32_e32 v2, 6, v1
	v_lshl_add_u32 v3, v2, 1, v187
	ds_read_u16 v3, v3
	s_waitcnt lgkmcnt(0)
	v_lshlrev_b32_e32 v3, 16, v3
	v_mul_f32_e32 v3, v0, v3
	v_cvt_pk_bf16_f32 v4, v3, s0
	v_mad_u64_u32 v[2:3], s[42:43], v2, s24, v[48:49]
	ds_write_b16 v2, v4
	v_add_u32_e32 v2, 0x100, v1
	v_ashrrev_i32_e32 v2, 6, v2
	v_lshl_add_u32 v3, v2, 1, v187
	ds_read_u16 v3, v3
	v_add_u32_e32 v1, 0x200, v1
	v_ashrrev_i32_e32 v1, 6, v1
	s_waitcnt lgkmcnt(0)
	v_lshlrev_b32_e32 v3, 16, v3
	v_mul_f32_e32 v3, v0, v3
	v_cvt_pk_bf16_f32 v4, v3, s0
	v_mad_u64_u32 v[2:3], s[42:43], v2, s24, v[48:49]
	ds_write_b16 v2, v4
	v_lshl_add_u32 v2, v1, 1, v187
	ds_read_u16 v2, v2
	s_waitcnt lgkmcnt(0)
	v_lshlrev_b32_e32 v2, 16, v2
	v_mul_f32_e32 v2, v0, v2
	v_cvt_pk_bf16_f32 v4, v2, s0
	v_mad_u64_u32 v[2:3], s[42:43], v1, s24, v[48:49]
	ds_write_b16 v2, v4
	s_cbranch_scc0 .LBB0_870
	s_cmp_gt_i32 s38, -1
	s_cbranch_scc0 .LBB0_877
	s_bfe_u32 s41, s38, 0x70002
	s_lshl_b32 s22, s38, 4
	s_and_b32 s22, s22, 0x7fffe000
	s_lshl_b32 s23, s41, 6
	s_or_b32 s22, s23, s22
	s_mul_hi_u32 s23, s22, 0x1800
	s_mulk_i32 s22, 0x1800
	s_add_u32 s22, s10, s22
	s_addc_u32 s23, s11, s23
	s_lshl_b32 s42, s38, 8
	s_and_b32 s42, s42, 0x300
	s_add_u32 s22, s22, s42
	s_addc_u32 s23, s23, 0
	s_cmp_lg_u32 s41, 0
	v_readlane_b32 s86, v244, 49
	s_cselect_b64 s[42:43], -1, 0
	v_readlane_b32 s87, v244, 50
	s_or_b64 s[42:43], s[42:43], s[86:87]
	v_mov_b32_e32 v0, 0
	v_mov_b32_e32 v1, 0
	s_and_saveexec_b64 s[86:87], s[42:43]
	s_cbranch_execz .LBB0_874
	v_lshl_add_u64 v[2:3], s[22:23], 0, v[50:51]
	v_lshl_add_u64 v[2:3], v[2:3], 0, v[52:53]
	s_movk_i32 s42, 0xc000
	v_lshl_add_u64 v[2:3], v[2:3], 0, v[54:55]
	s_mov_b32 s43, -1
	v_lshl_add_u64 v[2:3], v[2:3], 0, s[42:43]
	global_load_dword v245, v[2:3], off
.LBB0_874:
	s_or_b64 exec, exec, s[86:87]
	s_mov_b64 s[86:87], exec
	v_readlane_b32 s42, v244, 51
	v_readlane_b32 s43, v244, 52
	s_and_b64 s[42:43], s[86:87], s[42:43]
	s_mov_b64 exec, s[42:43]
	s_cbranch_execz .LBB0_876
	v_lshl_add_u64 v[2:3], s[22:23], 0, v[58:59]
	v_lshl_add_u64 v[2:3], v[2:3], 0, v[60:61]
	s_movk_i32 s22, 0xc000
	v_lshl_add_u64 v[2:3], v[2:3], 0, v[62:63]
	s_mov_b32 s23, -1
	v_lshl_add_u64 v[2:3], v[2:3], 0, s[22:23]
	global_load_dword v255, v[2:3], off
.LBB0_876:
	s_or_b64 exec, exec, s[86:87]
	s_nop 0
